# sample-combine pass: w_uv head slice staged with its 8 loads per thread in flight together
# baseline (speedup 1.0000x reference)
; #define LAS __attribute__((address_space(3)))
; __device__ __forceinline__ void p6_combine(Frame& F) {
;     ...
;         for (int i = tid; i < 4096; i += NWAVES * 64) { const int c = i >> 4, d4 = i & 15; *(LAS f32x4*)(WS_ + c * 64 + d4 * 4) = *(const f32x4*)(w_uv + (size_t)c * 512 + h * 64 + d4 * 4); }
.LBB0_1174:
	s_and_b32 s62, s81, 7
	s_and_saveexec_b64 s[46:47], s[8:9]
	s_cbranch_execz .LBB0_1177
	s_lshl_b32 s24, s62, 8
	s_waitcnt lgkmcnt(0)
	s_add_u32 s48, s42, s24
	s_addc_u32 s49, s43, 0
	s_mov_b64 s[50:51], 0
	v_mov_b32_e32 v2, v166
	v_mov_b32_e32 v3, v1
	v_lshrrev_b32_e32 v176, 4, v1
	v_lshlrev_b32_e32 v177, 4, v1
	v_and_b32_e32 v177, 0xf0, v177
	v_lshl_add_u32 v178, v176, 11, v177
	v_lshl_add_u32 v179, v176, 8, v177
	s_mov_b64 s[88:89], s[48:49]
	global_load_dwordx4 v[180:183], v178, s[88:89]
	s_add_u32 s88, s88, 0x10000
	s_addc_u32 s89, s89, 0
	global_load_dwordx4 v[184:187], v178, s[88:89]
	s_add_u32 s88, s88, 0x10000
	s_addc_u32 s89, s89, 0
	global_load_dwordx4 v[188:191], v178, s[88:89]
	s_add_u32 s88, s88, 0x10000
	s_addc_u32 s89, s89, 0
	global_load_dwordx4 v[192:195], v178, s[88:89]
	s_add_u32 s88, s88, 0x10000
	s_addc_u32 s89, s89, 0
	global_load_dwordx4 v[196:199], v178, s[88:89]
	s_add_u32 s88, s88, 0x10000
	s_addc_u32 s89, s89, 0
	global_load_dwordx4 v[200:203], v178, s[88:89]
	s_add_u32 s88, s88, 0x10000
	s_addc_u32 s89, s89, 0
	global_load_dwordx4 v[204:207], v178, s[88:89]
	s_add_u32 s88, s88, 0x10000
	s_addc_u32 s89, s89, 0
	global_load_dwordx4 v[208:211], v178, s[88:89]
	s_waitcnt vmcnt(7)
	ds_write_b128 v179, v[180:183]
	s_waitcnt vmcnt(6)
	ds_write_b128 v179, v[184:187] offset:8192
	s_waitcnt vmcnt(5)
	ds_write_b128 v179, v[188:191] offset:16384
	s_waitcnt vmcnt(4)
	ds_write_b128 v179, v[192:195] offset:24576
	s_waitcnt vmcnt(3)
	ds_write_b128 v179, v[196:199] offset:32768
	s_waitcnt vmcnt(2)
	ds_write_b128 v179, v[200:203] offset:40960
	s_waitcnt vmcnt(1)
	ds_write_b128 v179, v[204:207] offset:49152
	s_waitcnt vmcnt(0)
	ds_write_b128 v179, v[208:211] offset:57344
